# final phase: nt (streaming) policy on the once-read residual x loads and the once-written output stores
# baseline (speedup 1.0000x reference)
; __device__ __forceinline__ float bf_lo(unsigned u) { return __uint_as_float(u << 16); }
; __device__ __forceinline__ float bf_hi(unsigned u) { return __uint_as_float(u & 0xffff0000u); }
; __device__ __forceinline__ void phase_final(const Params& p) {
;     ...
;     for (int row = blockIdx.x * 8 + wid; row < MT; row += gridDim.x * 8) {
;         const bf16_t* yr = p.QG + (size_t)row * DM; float* xr = p.out + (size_t)row * DM; const float* xi = xrow(p, row);
;         u32x4 v[4]; f32x4 y0[4], y1[4]; float ss = 0.f;
; #pragma unroll
;         for (int i = 0; i < 4; ++i) { const int c = i * 512 + lane * 8; v[i] = *(const u32x4*)(yr + c); y0[i] = *(const f32x4*)(xi + c); y1[i] = *(const f32x4*)(xi + c + 4); }
; #pragma unroll
;         for (int i = 0; i < 4; ++i) {
;             y0[i] += (f32x4){bf_lo(v[i].x), bf_hi(v[i].x), bf_lo(v[i].y), bf_hi(v[i].y)}; y1[i] += (f32x4){bf_lo(v[i].z), bf_hi(v[i].z), bf_lo(v[i].w), bf_hi(v[i].w)};
;             ss += y0[i][0] * y0[i][0] + y0[i][1] * y0[i][1] + y0[i][2] * y0[i][2] + y0[i][3] * y0[i][3] + y1[i][0] * y1[i][0] + y1[i][1] * y1[i][1] + y1[i][2] * y1[i][2] + y1[i][3] * y1[i][3]; }
.LBB0_618:
	v_ashrrev_i32_e32 v129, 31, v128
	v_add_u32_e32 v37, 0xffff8000, v128
	v_cmp_gt_i32_e32 vcc, s3, v128
	v_lshlrev_b64 v[48:49], 12, v[128:129]
	v_mov_b32_e32 v39, s11
	v_mov_b32_e32 v47, s9
	v_mov_b32_e32 v64, s10
	v_mov_b32_e32 v66, s8
	v_cndmask_b32_e32 v63, 0, v129, vcc
	v_cndmask_b32_e32 v62, v37, v128, vcc
	v_lshl_add_u64 v[60:61], v[34:35], 0, v[48:49]
	v_cndmask_b32_e32 v65, v39, v47, vcc
	v_cndmask_b32_e32 v64, v64, v66, vcc
	v_lshlrev_b64 v[66:67], 13, v[62:63]
	global_load_dwordx4 v[48:51], v[60:61], off
	global_load_dwordx4 v[52:55], v[60:61], off offset:1024
	v_lshl_add_u64 v[88:89], v[64:65], 0, v[66:67]
	v_lshl_add_u64 v[80:81], v[88:89], 0, v[32:33]
	global_load_dwordx4 v[56:59], v[60:61], off offset:2048
	v_mov_b32_e32 v37, v33
	global_load_dwordx4 v[60:63], v[60:61], off offset:3072
	s_nop 0
	global_load_dwordx4 v[64:67], v[80:81], off nt
	global_load_dwordx4 v[68:71], v[80:81], off offset:16 nt
	global_load_dwordx4 v[72:75], v[80:81], off offset:2048 nt
	global_load_dwordx4 v[76:79], v[80:81], off offset:2064 nt
	v_lshl_add_u64 v[90:91], v[88:89], 0, v[36:37]
	global_load_dwordx4 v[80:83], v[90:91], off nt
	global_load_dwordx4 v[84:87], v[90:91], off offset:16 nt
	v_mov_b32_e32 v39, v33
	v_lshl_add_u64 v[96:97], v[88:89], 0, v[38:39]
	global_load_dwordx4 v[88:91], v[96:97], off nt
	global_load_dwordx4 v[92:95], v[96:97], off offset:16 nt
	s_waitcnt vmcnt(11)
	v_lshlrev_b32_e32 v96, 16, v48
	v_and_b32_e32 v97, 0xffff0000, v48
	v_lshlrev_b32_e32 v48, 16, v49
	v_and_b32_e32 v49, 0xffff0000, v49
	v_lshlrev_b32_e32 v98, 16, v50
	v_and_b32_e32 v99, 0xffff0000, v50
	v_lshlrev_b32_e32 v50, 16, v51
	v_and_b32_e32 v51, 0xffff0000, v51
	s_waitcnt vmcnt(10)
	v_lshlrev_b32_e32 v100, 16, v52
	v_and_b32_e32 v101, 0xffff0000, v52
	v_lshlrev_b32_e32 v102, 16, v54
	v_and_b32_e32 v103, 0xffff0000, v54
	v_lshlrev_b32_e32 v54, 16, v55
	v_and_b32_e32 v55, 0xffff0000, v55
	s_waitcnt vmcnt(7)
	v_pk_add_f32 v[48:49], v[66:67], v[48:49]
	v_pk_add_f32 v[64:65], v[64:65], v[96:97]
	s_waitcnt vmcnt(6)
	v_pk_add_f32 v[66:67], v[70:71], v[50:51]
	s_waitcnt vmcnt(5)
	v_pk_add_f32 v[70:71], v[72:73], v[100:101]
	v_lshlrev_b32_e32 v52, 16, v53
	v_and_b32_e32 v53, 0xffff0000, v53
	s_waitcnt vmcnt(4)
	v_pk_add_f32 v[54:55], v[78:79], v[54:55]
	v_mov_b32_e32 v78, v65
	v_mov_b32_e32 v79, v71
	v_lshlrev_b32_e32 v104, 16, v56
	v_and_b32_e32 v105, 0xffff0000, v56
	v_pk_add_f32 v[52:53], v[74:75], v[52:53]
	v_mov_b32_e32 v50, v64
	v_mov_b32_e32 v51, v70
	v_pk_mul_f32 v[78:79], v[78:79], v[78:79]
	v_lshlrev_b32_e32 v56, 16, v57
	v_and_b32_e32 v57, 0xffff0000, v57
	s_waitcnt vmcnt(3)
	v_pk_add_f32 v[74:75], v[80:81], v[104:105]
	v_mov_b32_e32 v80, v48
	v_mov_b32_e32 v81, v52
	v_pk_fma_f32 v[50:51], v[50:51], v[50:51], v[78:79]
	v_lshlrev_b32_e32 v106, 16, v58
	v_and_b32_e32 v107, 0xffff0000, v58
	v_lshlrev_b32_e32 v108, 16, v60
	v_and_b32_e32 v109, 0xffff0000, v60
	v_pk_add_f32 v[68:69], v[68:69], v[98:99]
	v_pk_add_f32 v[72:73], v[76:77], v[102:103]
	v_pk_add_f32 v[56:57], v[82:83], v[56:57]
	v_mov_b32_e32 v82, v49
	v_mov_b32_e32 v83, v53
	v_pk_fma_f32 v[50:51], v[80:81], v[80:81], v[50:51]
	s_waitcnt vmcnt(2)
	v_pk_add_f32 v[76:77], v[84:85], v[106:107]
	v_mov_b32_e32 v84, v68
	v_mov_b32_e32 v85, v72
	v_pk_fma_f32 v[50:51], v[82:83], v[82:83], v[50:51]
	s_waitcnt vmcnt(1)
	v_pk_add_f32 v[78:79], v[88:89], v[108:109]
	v_lshlrev_b32_e32 v60, 16, v61
	v_pk_fma_f32 v[50:51], v[84:85], v[84:85], v[50:51]
	v_and_b32_e32 v61, 0xffff0000, v61
	v_mov_b32_e32 v84, v75
	v_mov_b32_e32 v85, v79
	v_pk_add_f32 v[60:61], v[90:91], v[60:61]
	v_mov_b32_e32 v82, v74
	v_mov_b32_e32 v83, v78
	v_pk_mul_f32 v[84:85], v[84:85], v[84:85]
	v_lshlrev_b32_e32 v80, 16, v62
	v_and_b32_e32 v81, 0xffff0000, v62
	v_pk_fma_f32 v[82:83], v[82:83], v[82:83], v[84:85]
	v_mov_b32_e32 v84, v56
	v_mov_b32_e32 v85, v60
	v_lshlrev_b32_e32 v58, 16, v59
	v_and_b32_e32 v59, 0xffff0000, v59
	s_waitcnt vmcnt(0)
; __device__ __forceinline__ void phase_final(const Params& p) {
;     ...
;             ss += y0[i][0] * y0[i][0] + y0[i][1] * y0[i][1] + y0[i][2] * y0[i][2] + y0[i][3] * y0[i][3] + y1[i][0] * y1[i][0] + y1[i][1] * y1[i][1] + y1[i][2] * y1[i][2] + y1[i][3] * y1[i][3]; }
;         ss = wave_sum(ss);
;         const float rs = rsqrtf(ss * (1.0f / DM) + 1e-6f);
; #pragma unroll
;         for (int i = 0; i < 4; ++i) { const int c = i * 512 + lane * 8;
;             *(f32x4*)(xr + c) = y0[i] * rs * fg0[i]; *(f32x4*)(xr + c + 4) = y1[i] * rs * fg1[i]; }
	v_pk_add_f32 v[80:81], v[92:93], v[80:81]
	v_pk_fma_f32 v[82:83], v[84:85], v[84:85], v[82:83]
	v_mov_b32_e32 v84, v57
	v_mov_b32_e32 v85, v61
	v_pk_add_f32 v[58:59], v[86:87], v[58:59]
	v_mov_b32_e32 v86, v69
	v_mov_b32_e32 v87, v73
	v_lshlrev_b32_e32 v62, 16, v63
	v_and_b32_e32 v63, 0xffff0000, v63
	v_pk_fma_f32 v[82:83], v[84:85], v[84:85], v[82:83]
	v_mov_b32_e32 v84, v76
	v_mov_b32_e32 v85, v80
	v_mov_b32_e32 v96, v66
	v_mov_b32_e32 v97, v54
	v_pk_fma_f32 v[50:51], v[86:87], v[86:87], v[50:51]
	v_pk_add_f32 v[62:63], v[94:95], v[62:63]
	v_pk_fma_f32 v[82:83], v[84:85], v[84:85], v[82:83]
	v_mov_b32_e32 v84, v77
	v_mov_b32_e32 v85, v81
	v_mov_b32_e32 v98, v67
	v_mov_b32_e32 v99, v55
	v_pk_fma_f32 v[50:51], v[96:97], v[96:97], v[50:51]
	v_pk_fma_f32 v[82:83], v[84:85], v[84:85], v[82:83]
	v_mov_b32_e32 v84, v58
	v_mov_b32_e32 v85, v62
	v_pk_fma_f32 v[50:51], v[98:99], v[98:99], v[50:51]
	v_pk_fma_f32 v[82:83], v[84:85], v[84:85], v[82:83]
	v_mov_b32_e32 v84, v59
	v_mov_b32_e32 v85, v63
	v_pk_fma_f32 v[82:83], v[84:85], v[84:85], v[82:83]
	v_add_f32_e32 v47, v50, v51
	v_add_f32_e32 v47, v47, v82
	v_add_f32_e32 v47, v47, v83
	ds_bpermute_b32 v50, v40, v47
	s_waitcnt lgkmcnt(0)
	v_add_f32_e32 v47, v47, v50
	ds_bpermute_b32 v50, v41, v47
	s_waitcnt lgkmcnt(0)
	v_add_f32_e32 v47, v47, v50
	ds_bpermute_b32 v50, v42, v47
	s_waitcnt lgkmcnt(0)
	v_add_f32_e32 v47, v47, v50
	ds_bpermute_b32 v50, v43, v47
	s_waitcnt lgkmcnt(0)
	v_add_f32_e32 v47, v47, v50
	ds_bpermute_b32 v50, v44, v47
	s_waitcnt lgkmcnt(0)
	v_add_f32_e32 v47, v47, v50
	ds_bpermute_b32 v50, v45, v47
	s_waitcnt lgkmcnt(0)
	v_add_f32_e32 v47, v47, v50
	v_fmamk_f32 v47, v47, 0x3a000000, v46
	v_mul_f32_e32 v50, 0x4b800000, v47
	v_cmp_gt_f32_e32 vcc, s4, v47
	s_nop 1
	v_cndmask_b32_e32 v47, v47, v50, vcc
	v_rsq_f32_e32 v47, v47
	v_lshlrev_b64 v[50:51], 13, v[128:129]
	v_lshl_add_u64 v[82:83], s[6:7], 0, v[50:51]
	v_add_u32_e32 v128, s2, v128
	v_mul_f32_e32 v50, 0x45800000, v47
	v_cndmask_b32_e32 v84, v47, v50, vcc
	v_pk_mul_f32 v[64:65], v[64:65], v[84:85] op_sel_hi:[1,0]
	v_pk_mul_f32 v[48:49], v[48:49], v[84:85] op_sel_hi:[1,0]
	v_cmp_lt_i32_e32 vcc, s5, v128
	v_pk_mul_f32 v[50:51], v[6:7], v[48:49]
	v_pk_mul_f32 v[48:49], v[4:5], v[64:65]
	v_lshl_add_u64 v[64:65], v[82:83], 0, v[32:33]
	global_store_dwordx4 v[64:65], v[48:51], off nt
	s_or_b64 s[0:1], vcc, s[0:1]
	s_nop 0
	v_pk_mul_f32 v[48:49], v[68:69], v[84:85] op_sel_hi:[1,0]
	v_pk_mul_f32 v[50:51], v[66:67], v[84:85] op_sel_hi:[1,0]
	v_pk_mul_f32 v[48:49], v[0:1], v[48:49]
	v_pk_mul_f32 v[50:51], v[2:3], v[50:51]
	global_store_dwordx4 v[64:65], v[48:51], off offset:16 nt
	s_nop 1
	v_pk_mul_f32 v[48:49], v[70:71], v[84:85] op_sel_hi:[1,0]
	v_pk_mul_f32 v[50:51], v[52:53], v[84:85] op_sel_hi:[1,0]
	v_pk_mul_f32 v[48:49], v[12:13], v[48:49]
	v_pk_mul_f32 v[50:51], v[14:15], v[50:51]
	global_store_dwordx4 v[64:65], v[48:51], off offset:2048 nt
	v_lshl_add_u64 v[52:53], v[82:83], 0, v[36:37]
	s_nop 0
	v_pk_mul_f32 v[48:49], v[72:73], v[84:85] op_sel_hi:[1,0]
	v_pk_mul_f32 v[50:51], v[54:55], v[84:85] op_sel_hi:[1,0]
	v_pk_mul_f32 v[48:49], v[8:9], v[48:49]
	v_pk_mul_f32 v[50:51], v[10:11], v[50:51]
	global_store_dwordx4 v[64:65], v[48:51], off offset:2064 nt
	s_nop 1
	v_pk_mul_f32 v[48:49], v[74:75], v[84:85] op_sel_hi:[1,0]
	v_pk_mul_f32 v[50:51], v[56:57], v[84:85] op_sel_hi:[1,0]
	v_pk_mul_f32 v[48:49], v[20:21], v[48:49]
	v_pk_mul_f32 v[50:51], v[22:23], v[50:51]
	global_store_dwordx4 v[52:53], v[48:51], off nt
	s_nop 1
	v_pk_mul_f32 v[48:49], v[76:77], v[84:85] op_sel_hi:[1,0]
	v_pk_mul_f32 v[50:51], v[58:59], v[84:85] op_sel_hi:[1,0]
	v_pk_mul_f32 v[48:49], v[16:17], v[48:49]
	v_pk_mul_f32 v[50:51], v[18:19], v[50:51]
	global_store_dwordx4 v[52:53], v[48:51], off offset:16 nt
	v_lshl_add_u64 v[52:53], v[82:83], 0, v[38:39]
	s_nop 0
	v_pk_mul_f32 v[48:49], v[78:79], v[84:85] op_sel_hi:[1,0]
	v_pk_mul_f32 v[50:51], v[60:61], v[84:85] op_sel_hi:[1,0]
	v_pk_mul_f32 v[48:49], v[28:29], v[48:49]
	v_pk_mul_f32 v[50:51], v[30:31], v[50:51]
	global_store_dwordx4 v[52:53], v[48:51], off nt
	s_nop 1
	v_pk_mul_f32 v[48:49], v[80:81], v[84:85] op_sel_hi:[1,0]
	v_pk_mul_f32 v[50:51], v[62:63], v[84:85] op_sel_hi:[1,0]
	v_pk_mul_f32 v[48:49], v[24:25], v[48:49]
	v_pk_mul_f32 v[50:51], v[26:27], v[50:51]
	global_store_dwordx4 v[52:53], v[48:51], off offset:16 nt
	s_andn2_b64 exec, exec, s[0:1]
	s_cbranch_execnz .LBB0_618
